# speedup vs baseline: 1.0253x; 1.0083x over previous
; #define STAGE_A(Pp, br, kt) do { const char* _g = (const char*)(A + (size_t)(br) * lda + a_col(amode, kt)); \
;     __builtin_amdgcn_global_load_lds((const unsigned*)(_g + aoffb), (LAS unsigned*)((Pp) + tid * 16), 16, 0, 0); \
;     __builtin_amdgcn_global_load_lds((const unsigned*)(_g + (size_t)128 * lda + aoffb), (LAS unsigned*)((Pp) + tid * 16 + 8192), 16, 0, 0); } while (0)
; #define LDA(dst, b, h) for (int m = 0; m < 4; ++m) for (int k = 0; k < 2; ++k) dst[m][k] = *(const LAS bf16x8*)(SA(b, h) + lds_byte(wr * 64 + m * 16 + fr, k * 32 + fq * 8))
; #define LDB(dst, b, h) for (int n = 0; n < 2; ++n) for (int k = 0; k < 2; ++k) dst[n][k] = *(const LAS bf16x8*)(SB(b, h) + lds_byte(wc * 32 + n * 16 + fr, k * 32 + fq * 8))
; #define MMA(ai, bj, At_, Bt_) do { __builtin_amdgcn_s_setprio(1); \
;     for (int m = 0; m < 4; ++m) for (int n = 0; n < 2; ++n) for (int k = 0; k < 2; ++k) \
;         acc[ai][bj][m][n] = MFMA16(Bt_[n][k], At_[m][k], acc[ai][bj][m][n]); \
;     __builtin_amdgcn_s_setprio(0); } while (0)
; #define WAIT_V(n) asm volatile("s_waitcnt vmcnt(" #n ")" ::: "memory")
; #define WAIT_L(n) asm volatile("s_waitcnt lgkmcnt(" #n ")" ::: "memory")
; #define BAR __builtin_amdgcn_s_barrier()
; #define SCHED __builtin_amdgcn_sched_barrier(0)
; DI void gemm_phase(const Params& P, const GemmJob& J, LAS unsigned char* lds) {
;     ...
;         for (;;) {
;             const int brow = pm * BM, bcol = pn * BM;
;             const int Ln = L + gridDim.x; int pm2 = pm, pn2 = pn;
;             const bool has_next = Ln < nwg;
;             if (has_next) TILE_COORDS(Ln, pm2, pn2);
;             const int brow2 = pm2 * BM, bcol2 = pn2 * BM;
;             for (int t = 0; t < nt; t += 2) {
;                 const bool last = (t == nt - 2);
;                 const int r2 = last ? brow2 : brow, c2 = last ? bcol2 : bcol, k2 = last ? 0 : t + 2, k3 = k2 + 1;
;                 LDB(B0, 0, 0); LDB(B1, 0, 1); SCHED; LDA(At, 0, 0); STAGE_A(SA(1, 1), brow + HALF, t + 1);
;                 WAIT_V(8); WAIT_L(0); BAR; MMA(0, 0, At, B0); MMA(0, 1, At, B1); BAR; SCHED;
.LBB0_319:
	s_or_b32 s3, s37, 0x80
	s_ashr_i32 s20, s37, 31
	s_mul_hi_u32 s42, s3, s44
	s_mul_i32 s20, s20, s44
	s_add_i32 s97, s42, s20
	s_mul_i32 s96, s3, s44
	s_lshl_b64 s[96:97], s[96:97], 1
	s_add_u32 s3, s10, s96
	v_mov_b32_e32 v0, 0
	s_addc_u32 s89, s11, s97
	s_mov_b32 s95, 0
	s_mov_b32 s96, 64
	s_mov_b32 s97, 2
	v_mov_b32_e32 v1, v0
	v_mov_b32_e32 v2, v0
	v_mov_b32_e32 v3, v0
	v_mov_b32_e32 v8, v0
	v_mov_b32_e32 v9, v0
	v_mov_b32_e32 v10, v0
	v_mov_b32_e32 v11, v0
	v_mov_b32_e32 v16, v0
	v_mov_b32_e32 v17, v0
	v_mov_b32_e32 v18, v0
	v_mov_b32_e32 v19, v0
	v_mov_b32_e32 v24, v0
	v_mov_b32_e32 v25, v0
	v_mov_b32_e32 v26, v0
	v_mov_b32_e32 v27, v0
	v_mov_b32_e32 v32, v0
	v_mov_b32_e32 v33, v0
	v_mov_b32_e32 v34, v0
	v_mov_b32_e32 v35, v0
	v_mov_b32_e32 v40, v0
	v_mov_b32_e32 v41, v0
	v_mov_b32_e32 v42, v0
	v_mov_b32_e32 v43, v0
	v_mov_b32_e32 v48, v0
	v_mov_b32_e32 v49, v0
	v_mov_b32_e32 v50, v0
	v_mov_b32_e32 v51, v0
	v_mov_b32_e32 v56, v0
	v_mov_b32_e32 v57, v0
	v_mov_b32_e32 v58, v0
	v_mov_b32_e32 v59, v0
	v_mov_b32_e32 v4, v0
	v_mov_b32_e32 v5, v0
	v_mov_b32_e32 v6, v0
	v_mov_b32_e32 v7, v0
	v_mov_b32_e32 v12, v0
	v_mov_b32_e32 v13, v0
	v_mov_b32_e32 v14, v0
	v_mov_b32_e32 v15, v0
	v_mov_b32_e32 v20, v0
	v_mov_b32_e32 v21, v0
	v_mov_b32_e32 v22, v0
	v_mov_b32_e32 v23, v0
	v_mov_b32_e32 v28, v0
	v_mov_b32_e32 v29, v0
	v_mov_b32_e32 v30, v0
	v_mov_b32_e32 v31, v0
	v_mov_b32_e32 v36, v0
	v_mov_b32_e32 v37, v0
	v_mov_b32_e32 v38, v0
	v_mov_b32_e32 v39, v0
	v_mov_b32_e32 v44, v0
	v_mov_b32_e32 v45, v0
	v_mov_b32_e32 v46, v0
	v_mov_b32_e32 v47, v0
	v_mov_b32_e32 v52, v0
	v_mov_b32_e32 v53, v0
	v_mov_b32_e32 v54, v0
	v_mov_b32_e32 v55, v0
	v_mov_b32_e32 v60, v0
	v_mov_b32_e32 v61, v0
	v_mov_b32_e32 v62, v0
	v_mov_b32_e32 v63, v0
	v_mov_b32_e32 v64, v0
	v_mov_b32_e32 v65, v0
	v_mov_b32_e32 v66, v0
	v_mov_b32_e32 v67, v0
	v_mov_b32_e32 v72, v0
	v_mov_b32_e32 v73, v0
	v_mov_b32_e32 v74, v0
	v_mov_b32_e32 v75, v0
	v_mov_b32_e32 v80, v0
	v_mov_b32_e32 v81, v0
	v_mov_b32_e32 v82, v0
	v_mov_b32_e32 v83, v0
	v_mov_b32_e32 v88, v0
	v_mov_b32_e32 v89, v0
	v_mov_b32_e32 v90, v0
	v_mov_b32_e32 v91, v0
	v_mov_b32_e32 v96, v0
	v_mov_b32_e32 v97, v0
	v_mov_b32_e32 v98, v0
	v_mov_b32_e32 v99, v0
	v_mov_b32_e32 v104, v0
	v_mov_b32_e32 v105, v0
	v_mov_b32_e32 v106, v0
	v_mov_b32_e32 v107, v0
	v_mov_b32_e32 v112, v0
	v_mov_b32_e32 v113, v0
	v_mov_b32_e32 v114, v0
	v_mov_b32_e32 v115, v0
	v_mov_b32_e32 v120, v0
	v_mov_b32_e32 v121, v0
	v_mov_b32_e32 v122, v0
	v_mov_b32_e32 v123, v0
	v_mov_b32_e32 v68, v0
	v_mov_b32_e32 v69, v0
	v_mov_b32_e32 v70, v0
	v_mov_b32_e32 v71, v0
	v_mov_b32_e32 v76, v0
	v_mov_b32_e32 v77, v0
	v_mov_b32_e32 v78, v0
	v_mov_b32_e32 v79, v0
	v_mov_b32_e32 v84, v0
	v_mov_b32_e32 v85, v0
	v_mov_b32_e32 v86, v0
	v_mov_b32_e32 v87, v0
	v_mov_b32_e32 v92, v0
	v_mov_b32_e32 v93, v0
	v_mov_b32_e32 v94, v0
	v_mov_b32_e32 v95, v0
	v_mov_b32_e32 v100, v0
	v_mov_b32_e32 v101, v0
	v_mov_b32_e32 v102, v0
	v_mov_b32_e32 v103, v0
	v_mov_b32_e32 v108, v0
	v_mov_b32_e32 v109, v0
	v_mov_b32_e32 v110, v0
	v_mov_b32_e32 v111, v0
	v_mov_b32_e32 v116, v0
	v_mov_b32_e32 v117, v0
	v_mov_b32_e32 v118, v0
	v_mov_b32_e32 v119, v0
	v_mov_b32_e32 v124, v0
	v_mov_b32_e32 v125, v0
	v_mov_b32_e32 v126, v0
	v_mov_b32_e32 v127, v0
	v_readfirstlane_b32 s100, v140
.LBB0_320:
	ds_read_b128 v[132:135], v151
	ds_read_b128 v[158:161], v151 offset:1024
	ds_read_b128 v[162:165], v151 offset:2048
	ds_read_b128 v[166:169], v151 offset:3072
	ds_read_b128 v[170:173], v152
	ds_read_b128 v[174:177], v152 offset:1024
	ds_read_b128 v[178:181], v152 offset:2048
	ds_read_b128 v[186:189], v152 offset:3072
	s_add_i32 s20, s97, -2
	s_cmp_eq_u32 s45, s97
	s_cselect_b32 s42, s94, s36
	s_cselect_b32 s98, s2, s37
	s_cselect_b32 s99, 0, s97
	s_lshl_b32 s28, s42, 8
	s_cmp_gt_u32 s20, 15
	s_cselect_b32 s20, s39, 0x400
	s_and_b64 vcc, s[4:5], exec
	s_cselect_b32 s20, s20, 0
	s_and_b64 vcc, s[48:49], exec
	s_cselect_b32 s29, s95, 0
	s_add_i32 s20, s20, s29
	s_add_i32 vcc_lo, s96, s20
	s_ashr_i32 vcc_hi, vcc_lo, 31
	s_lshl_b64 vcc, vcc, 1
	s_add_u32 vcc_lo, s3, vcc_lo
	s_addc_u32 vcc_hi, s89, vcc_hi
	v_add_u32_e32 v184, s47, v150
	s_add_i32 m0, s100, 0xc000
	ds_read_b128 v[190:193], v153
	ds_read_b128 v[208:211], v153 offset:1024
	ds_read_b128 v[212:215], v184
	ds_read_b128 v[216:219], v184 offset:1024
	ds_read_b128 v[220:223], v154
	ds_read_b128 v[224:227], v154 offset:1024
	ds_read_b128 v[228:231], v155
	ds_read_b128 v[232:235], v155 offset:1024
	global_load_lds_dwordx4 v130, vcc
	s_add_u32 vcc_lo, vcc_lo, s52
	s_addc_u32 vcc_hi, vcc_hi, s53
	s_add_i32 m0, s100, 0xe000
	s_nop 0
	global_load_lds_dwordx4 v130, vcc
	s_waitcnt vmcnt(8)
	s_waitcnt lgkmcnt(0)
	s_barrier
; #define STAGE_A(Pp, br, kt) do { const char* _g = (const char*)(A + (size_t)(br) * lda + a_col(amode, kt)); \
;     __builtin_amdgcn_global_load_lds((const unsigned*)(_g + aoffb), (LAS unsigned*)((Pp) + tid * 16), 16, 0, 0); \
;     __builtin_amdgcn_global_load_lds((const unsigned*)(_g + (size_t)128 * lda + aoffb), (LAS unsigned*)((Pp) + tid * 16 + 8192), 16, 0, 0); } while (0)
; #define STAGE_B(Pp, br, kt) do { const char* _g = (const char*)(Bt + (size_t)(br) * K + (kt) * BK); \
;     __builtin_amdgcn_global_load_lds((const unsigned*)(_g + boffb), (LAS unsigned*)((Pp) + tid * 16), 16, 0, 0); \
;     __builtin_amdgcn_global_load_lds((const unsigned*)(_g + (size_t)128 * K + boffb), (LAS unsigned*)((Pp) + tid * 16 + 8192), 16, 0, 0); } while (0)
; #define LDA(dst, b, h) for (int m = 0; m < 4; ++m) for (int k = 0; k < 2; ++k) dst[m][k] = *(const LAS bf16x8*)(SA(b, h) + lds_byte(wr * 64 + m * 16 + fr, k * 32 + fq * 8))
; #define MMA(ai, bj, At_, Bt_) do { __builtin_amdgcn_s_setprio(1); \
;     for (int m = 0; m < 4; ++m) for (int n = 0; n < 2; ++n) for (int k = 0; k < 2; ++k) \
;         acc[ai][bj][m][n] = MFMA16(Bt_[n][k], At_[m][k], acc[ai][bj][m][n]); \
;     __builtin_amdgcn_s_setprio(0); } while (0)
; #define WAIT_V(n) asm volatile("s_waitcnt vmcnt(" #n ")" ::: "memory")
; #define WAIT_L(n) asm volatile("s_waitcnt lgkmcnt(" #n ")" ::: "memory")
; #define BAR __builtin_amdgcn_s_barrier()
; #define SCHED __builtin_amdgcn_sched_barrier(0)
; DI void gemm_phase(const Params& P, const GemmJob& J, LAS unsigned char* lds) {
;     ...
;                 WAIT_V(8); WAIT_L(0); BAR; MMA(0, 0, At, B0); MMA(0, 1, At, B1); BAR; SCHED;
;                 LDA(At, 0, 1); STAGE_B(SB(0, 0), c2, k2); STAGE_B(SB(0, 1), c2 + HALF, k2); STAGE_A(SA(0, 0), r2, k2);
	s_setprio 1
	s_waitcnt lgkmcnt(0)
	v_mfma_f32_16x16x32_bf16 v[124:127], v[132:135], v[190:193], v[124:127]
	v_mfma_f32_16x16x32_bf16 v[116:119], v[162:165], v[190:193], v[116:119]
	v_mfma_f32_16x16x32_bf16 v[108:111], v[132:135], v[212:215], v[108:111]
	v_mfma_f32_16x16x32_bf16 v[100:103], v[162:165], v[212:215], v[100:103]
	v_mfma_f32_16x16x32_bf16 v[92:95], v[132:135], v[220:223], v[92:95]
	v_mfma_f32_16x16x32_bf16 v[84:87], v[162:165], v[220:223], v[84:87]
	v_mfma_f32_16x16x32_bf16 v[76:79], v[132:135], v[228:231], v[76:79]
	v_mfma_f32_16x16x32_bf16 v[68:71], v[162:165], v[228:231], v[68:71]
	v_mfma_f32_16x16x32_bf16 v[124:127], v[158:161], v[208:211], v[124:127]
	v_mfma_f32_16x16x32_bf16 v[116:119], v[166:169], v[208:211], v[116:119]
	v_mfma_f32_16x16x32_bf16 v[108:111], v[158:161], v[216:219], v[108:111]
	v_mfma_f32_16x16x32_bf16 v[100:103], v[166:169], v[216:219], v[100:103]
	v_mfma_f32_16x16x32_bf16 v[92:95], v[158:161], v[224:227], v[92:95]
	v_mfma_f32_16x16x32_bf16 v[84:87], v[166:169], v[224:227], v[84:87]
	v_mfma_f32_16x16x32_bf16 v[76:79], v[158:161], v[232:235], v[76:79]
	v_mfma_f32_16x16x32_bf16 v[68:71], v[166:169], v[232:235], v[68:71]
	s_setprio 0
	s_setprio 1
	v_mfma_f32_16x16x32_bf16 v[120:123], v[170:173], v[190:193], v[120:123]
	v_mfma_f32_16x16x32_bf16 v[112:115], v[178:181], v[190:193], v[112:115]
	v_mfma_f32_16x16x32_bf16 v[104:107], v[170:173], v[212:215], v[104:107]
	v_mfma_f32_16x16x32_bf16 v[96:99], v[178:181], v[212:215], v[96:99]
	v_mfma_f32_16x16x32_bf16 v[88:91], v[170:173], v[220:223], v[88:91]
	v_mfma_f32_16x16x32_bf16 v[80:83], v[178:181], v[220:223], v[80:83]
	v_mfma_f32_16x16x32_bf16 v[72:75], v[170:173], v[228:231], v[72:75]
	v_mfma_f32_16x16x32_bf16 v[64:67], v[178:181], v[228:231], v[64:67]
	v_mfma_f32_16x16x32_bf16 v[120:123], v[174:177], v[208:211], v[120:123]
	v_mfma_f32_16x16x32_bf16 v[112:115], v[186:189], v[208:211], v[112:115]
	v_mfma_f32_16x16x32_bf16 v[104:107], v[174:177], v[216:219], v[104:107]
	v_mfma_f32_16x16x32_bf16 v[96:99], v[186:189], v[216:219], v[96:99]
	v_mfma_f32_16x16x32_bf16 v[88:91], v[174:177], v[224:227], v[88:91]
	v_mfma_f32_16x16x32_bf16 v[80:83], v[186:189], v[224:227], v[80:83]
	v_mfma_f32_16x16x32_bf16 v[72:75], v[174:177], v[232:235], v[72:75]
	v_mfma_f32_16x16x32_bf16 v[64:67], v[186:189], v[232:235], v[64:67]
	s_setprio 0
	s_barrier
	s_ashr_i32 s20, s28, 31
	s_mul_i32 s29, s20, s46
	s_mul_hi_u32 s20, s28, s46
	s_add_i32 vcc_hi, s20, s29
	s_mul_i32 vcc_lo, s28, s46
	s_lshl_b64 vcc, vcc, 1
	s_add_u32 s42, s8, vcc_lo
	s_addc_u32 s43, s9, vcc_hi
	s_lshl_b32 s20, s99, 6
	s_lshl_b64 vcc, s[20:21], 1
	s_add_u32 s42, s42, vcc_lo
	s_addc_u32 s43, s43, vcc_hi
	v_lshl_add_u64 v[182:183], s[42:43], 0, v[128:129]
	s_add_u32 s42, s42, s50
	s_addc_u32 s43, s43, s51
	s_add_i32 m0, s100, 0x10000
	v_lshl_add_u64 v[236:237], s[42:43], 0, v[128:129]
	s_bitset1_b32 s28, 7
	ds_read_b128 v[190:193], v153 offset:16384
	ds_read_b128 v[208:211], v153 offset:17408
	ds_read_b128 v[212:215], v184 offset:16384
	ds_read_b128 v[216:219], v184 offset:17408
	ds_read_b128 v[220:223], v154 offset:16384
	ds_read_b128 v[224:227], v154 offset:17408
	ds_read_b128 v[228:231], v155 offset:16384
	ds_read_b128 v[232:235], v155 offset:17408
	global_load_lds_dwordx4 v[182:183], off
	s_add_i32 m0, s100, 0x12000
	s_mul_hi_u32 s42, s28, s46
	s_add_i32 s43, s42, s29
	s_mul_i32 s42, s28, s46
	s_lshl_b64 s[42:43], s[42:43], 1
	s_add_u32 s28, s8, s42
	s_addc_u32 s29, s9, s43
	s_add_u32 s42, s28, vcc_lo
	s_addc_u32 s43, s29, vcc_hi
	global_load_lds_dwordx4 v[236:237], off
	v_lshl_add_u64 v[238:239], s[42:43], 0, v[128:129]
	s_add_i32 m0, s100, 0x14000
	s_add_u32 s42, s42, s50
	s_addc_u32 s43, s43, s51
	global_load_lds_dwordx4 v[238:239], off
	s_add_i32 m0, s100, 0x16000
	s_ashr_i32 s28, s98, 31
	s_mul_i32 s28, s28, s44
	s_mul_hi_u32 s29, s98, s44
	v_lshl_add_u64 v[240:241], s[42:43], 0, v[128:129]
	s_add_i32 s43, s29, s28
	s_mul_i32 s42, s98, s44
	s_lshl_b64 s[42:43], s[42:43], 1
	s_add_u32 s29, s10, s42
	s_addc_u32 s85, s11, s43
	s_cmp_gt_u32 s99, 15
	s_cselect_b32 vcc_lo, s39, 0x400
	s_and_b64 s[42:43], s[4:5], exec
	s_cselect_b32 vcc_lo, vcc_lo, 0
	s_lshl_b32 s99, s99, 5
	s_and_b64 s[42:43], s[48:49], exec
	s_cselect_b32 s42, s99, 0
	s_add_i32 s42, vcc_lo, s42
	s_add_i32 s20, s42, s20
	s_lshl_b64 s[42:43], s[20:21], 1
	s_add_u32 vcc_lo, s29, s42
	s_addc_u32 vcc_hi, s85, s43
	global_load_lds_dwordx4 v[240:241], off
	s_mov_b32 m0, s100
	s_nop 0
	global_load_lds_dwordx4 v130, vcc
	s_add_u32 vcc_lo, vcc_lo, s52
	s_addc_u32 vcc_hi, vcc_hi, s53
	s_add_i32 m0, s100, 0x2000
	s_nop 0
	global_load_lds_dwordx4 v130, vcc
	s_waitcnt vmcnt(8)
	s_waitcnt lgkmcnt(0)
	s_barrier
; #define STAGE_A(Pp, br, kt) do { const char* _g = (const char*)(A + (size_t)(br) * lda + a_col(amode, kt)); \
;     __builtin_amdgcn_global_load_lds((const unsigned*)(_g + aoffb), (LAS unsigned*)((Pp) + tid * 16), 16, 0, 0); \
;     __builtin_amdgcn_global_load_lds((const unsigned*)(_g + (size_t)128 * lda + aoffb), (LAS unsigned*)((Pp) + tid * 16 + 8192), 16, 0, 0); } while (0)
; #define LDA(dst, b, h) for (int m = 0; m < 4; ++m) for (int k = 0; k < 2; ++k) dst[m][k] = *(const LAS bf16x8*)(SA(b, h) + lds_byte(wr * 64 + m * 16 + fr, k * 32 + fq * 8))
; #define LDB(dst, b, h) for (int n = 0; n < 2; ++n) for (int k = 0; k < 2; ++k) dst[n][k] = *(const LAS bf16x8*)(SB(b, h) + lds_byte(wc * 32 + n * 16 + fr, k * 32 + fq * 8))
; #define MMA(ai, bj, At_, Bt_) do { __builtin_amdgcn_s_setprio(1); \
;     for (int m = 0; m < 4; ++m) for (int n = 0; n < 2; ++n) for (int k = 0; k < 2; ++k) \
;         acc[ai][bj][m][n] = MFMA16(Bt_[n][k], At_[m][k], acc[ai][bj][m][n]); \
;     __builtin_amdgcn_s_setprio(0); } while (0)
; #define WAIT_V(n) asm volatile("s_waitcnt vmcnt(" #n ")" ::: "memory")
; #define WAIT_L(n) asm volatile("s_waitcnt lgkmcnt(" #n ")" ::: "memory")
; #define BAR __builtin_amdgcn_s_barrier()
; #define SCHED __builtin_amdgcn_sched_barrier(0)
; DI void gemm_phase(const Params& P, const GemmJob& J, LAS unsigned char* lds) {
;     ...
;                 WAIT_V(8); WAIT_L(0); BAR; MMA(1, 0, At, B0); MMA(1, 1, At, B1); BAR; SCHED;
;                 LDB(B0, 1, 0); LDB(B1, 1, 1); SCHED; LDA(At, 1, 0); STAGE_A(SA(0, 1), r2 + HALF, k2);
;                 WAIT_V(8); WAIT_L(0); BAR; MMA(0, 0, At, B0); MMA(0, 1, At, B1); BAR; SCHED;
	s_setprio 1
	s_waitcnt lgkmcnt(0)
	v_mfma_f32_16x16x32_bf16 v[60:63], v[132:135], v[190:193], v[60:63]
	v_mfma_f32_16x16x32_bf16 v[52:55], v[162:165], v[190:193], v[52:55]
	v_mfma_f32_16x16x32_bf16 v[44:47], v[132:135], v[212:215], v[44:47]
	v_mfma_f32_16x16x32_bf16 v[36:39], v[162:165], v[212:215], v[36:39]
	v_mfma_f32_16x16x32_bf16 v[28:31], v[132:135], v[220:223], v[28:31]
	v_mfma_f32_16x16x32_bf16 v[20:23], v[162:165], v[220:223], v[20:23]
	v_mfma_f32_16x16x32_bf16 v[12:15], v[132:135], v[228:231], v[12:15]
	v_mfma_f32_16x16x32_bf16 v[4:7], v[162:165], v[228:231], v[4:7]
	v_mfma_f32_16x16x32_bf16 v[60:63], v[158:161], v[208:211], v[60:63]
	v_mfma_f32_16x16x32_bf16 v[52:55], v[166:169], v[208:211], v[52:55]
	v_mfma_f32_16x16x32_bf16 v[44:47], v[158:161], v[216:219], v[44:47]
	v_mfma_f32_16x16x32_bf16 v[36:39], v[166:169], v[216:219], v[36:39]
	v_mfma_f32_16x16x32_bf16 v[28:31], v[158:161], v[224:227], v[28:31]
	v_mfma_f32_16x16x32_bf16 v[20:23], v[166:169], v[224:227], v[20:23]
	v_mfma_f32_16x16x32_bf16 v[12:15], v[158:161], v[232:235], v[12:15]
	v_mfma_f32_16x16x32_bf16 v[4:7], v[166:169], v[232:235], v[4:7]
	s_setprio 0
	s_setprio 1
	v_mfma_f32_16x16x32_bf16 v[56:59], v[170:173], v[190:193], v[56:59]
	v_mfma_f32_16x16x32_bf16 v[48:51], v[178:181], v[190:193], v[48:51]
	v_mfma_f32_16x16x32_bf16 v[40:43], v[170:173], v[212:215], v[40:43]
	v_mfma_f32_16x16x32_bf16 v[32:35], v[178:181], v[212:215], v[32:35]
	v_mfma_f32_16x16x32_bf16 v[24:27], v[170:173], v[220:223], v[24:27]
	v_mfma_f32_16x16x32_bf16 v[16:19], v[178:181], v[220:223], v[16:19]
	v_mfma_f32_16x16x32_bf16 v[8:11], v[170:173], v[228:231], v[8:11]
	v_mfma_f32_16x16x32_bf16 v[0:3], v[178:181], v[228:231], v[0:3]
	v_mfma_f32_16x16x32_bf16 v[56:59], v[174:177], v[208:211], v[56:59]
	v_mfma_f32_16x16x32_bf16 v[48:51], v[186:189], v[208:211], v[48:51]
	v_mfma_f32_16x16x32_bf16 v[40:43], v[174:177], v[216:219], v[40:43]
	v_mfma_f32_16x16x32_bf16 v[32:35], v[186:189], v[216:219], v[32:35]
	v_mfma_f32_16x16x32_bf16 v[24:27], v[174:177], v[224:227], v[24:27]
	v_mfma_f32_16x16x32_bf16 v[16:19], v[186:189], v[224:227], v[16:19]
	v_mfma_f32_16x16x32_bf16 v[8:11], v[174:177], v[232:235], v[8:11]
	v_mfma_f32_16x16x32_bf16 v[0:3], v[186:189], v[232:235], v[0:3]
	s_setprio 0
	s_barrier
	ds_read_b128 v[132:135], v156
	ds_read_b128 v[158:161], v156 offset:1024
	ds_read_b128 v[162:165], v156 offset:2048
	ds_read_b128 v[166:169], v156 offset:3072
	ds_read_b128 v[170:173], v157
	ds_read_b128 v[174:177], v157 offset:1024
	ds_read_b128 v[178:181], v157 offset:2048
	ds_read_b128 v[186:189], v157 offset:3072
	s_bitset1_b32 s98, 7
	s_mul_hi_u32 s99, s98, s44
	s_add_i32 s99, s99, s28
	s_mul_i32 s98, s98, s44
	s_lshl_b64 s[98:99], s[98:99], 1
	s_add_u32 s28, s10, s98
	s_addc_u32 s98, s11, s99
	s_add_u32 s42, s28, s42
	s_addc_u32 s43, s98, s43
	s_add_i32 m0, s100, 0x4000
	ds_read_b128 v[190:193], v153 offset:32768
	ds_read_b128 v[208:211], v153 offset:33792
	ds_read_b128 v[212:215], v184 offset:32768
	ds_read_b128 v[216:219], v184 offset:33792
	ds_read_b128 v[220:223], v154 offset:32768
	ds_read_b128 v[224:227], v154 offset:33792
	ds_read_b128 v[228:231], v155 offset:32768
	ds_read_b128 v[232:235], v155 offset:33792
	global_load_lds_dwordx4 v130, s[42:43]
	s_add_u32 s42, s42, s52
	s_addc_u32 s43, s43, s53
	s_add_i32 m0, s100, 0x6000
	s_nop 0
	global_load_lds_dwordx4 v130, s[42:43]
	s_waitcnt vmcnt(8)
	s_waitcnt lgkmcnt(0)
	s_barrier
	s_setprio 1
	s_waitcnt lgkmcnt(0)
	v_mfma_f32_16x16x32_bf16 v[124:127], v[132:135], v[190:193], v[124:127]
	v_mfma_f32_16x16x32_bf16 v[116:119], v[162:165], v[190:193], v[116:119]
	v_mfma_f32_16x16x32_bf16 v[108:111], v[132:135], v[212:215], v[108:111]
	v_mfma_f32_16x16x32_bf16 v[100:103], v[162:165], v[212:215], v[100:103]
	v_mfma_f32_16x16x32_bf16 v[92:95], v[132:135], v[220:223], v[92:95]
	v_mfma_f32_16x16x32_bf16 v[84:87], v[162:165], v[220:223], v[84:87]
	v_mfma_f32_16x16x32_bf16 v[76:79], v[132:135], v[228:231], v[76:79]
	v_mfma_f32_16x16x32_bf16 v[68:71], v[162:165], v[228:231], v[68:71]
	v_mfma_f32_16x16x32_bf16 v[124:127], v[158:161], v[208:211], v[124:127]
	v_mfma_f32_16x16x32_bf16 v[116:119], v[166:169], v[208:211], v[116:119]
	v_mfma_f32_16x16x32_bf16 v[108:111], v[158:161], v[216:219], v[108:111]
	v_mfma_f32_16x16x32_bf16 v[100:103], v[166:169], v[216:219], v[100:103]
	v_mfma_f32_16x16x32_bf16 v[92:95], v[158:161], v[224:227], v[92:95]
	v_mfma_f32_16x16x32_bf16 v[84:87], v[166:169], v[224:227], v[84:87]
	v_mfma_f32_16x16x32_bf16 v[76:79], v[158:161], v[232:235], v[76:79]
	v_mfma_f32_16x16x32_bf16 v[68:71], v[166:169], v[232:235], v[68:71]
	s_setprio 0
	s_setprio 1
	v_mfma_f32_16x16x32_bf16 v[120:123], v[170:173], v[190:193], v[120:123]
	v_mfma_f32_16x16x32_bf16 v[112:115], v[178:181], v[190:193], v[112:115]
	v_mfma_f32_16x16x32_bf16 v[104:107], v[170:173], v[212:215], v[104:107]
	v_mfma_f32_16x16x32_bf16 v[96:99], v[178:181], v[212:215], v[96:99]
	v_mfma_f32_16x16x32_bf16 v[88:91], v[170:173], v[220:223], v[88:91]
	v_mfma_f32_16x16x32_bf16 v[80:83], v[178:181], v[220:223], v[80:83]
	v_mfma_f32_16x16x32_bf16 v[72:75], v[170:173], v[228:231], v[72:75]
	v_mfma_f32_16x16x32_bf16 v[64:67], v[178:181], v[228:231], v[64:67]
	v_mfma_f32_16x16x32_bf16 v[120:123], v[174:177], v[208:211], v[120:123]
	v_mfma_f32_16x16x32_bf16 v[112:115], v[186:189], v[208:211], v[112:115]
	v_mfma_f32_16x16x32_bf16 v[104:107], v[174:177], v[216:219], v[104:107]
	v_mfma_f32_16x16x32_bf16 v[96:99], v[186:189], v[216:219], v[96:99]
	v_mfma_f32_16x16x32_bf16 v[88:91], v[174:177], v[224:227], v[88:91]
	v_mfma_f32_16x16x32_bf16 v[80:83], v[186:189], v[224:227], v[80:83]
	v_mfma_f32_16x16x32_bf16 v[72:75], v[174:177], v[232:235], v[72:75]
	v_mfma_f32_16x16x32_bf16 v[64:67], v[186:189], v[232:235], v[64:67]
	s_setprio 0
	s_barrier
; #define STAGE_A(Pp, br, kt) do { const char* _g = (const char*)(A + (size_t)(br) * lda + a_col(amode, kt)); \
;     __builtin_amdgcn_global_load_lds((const unsigned*)(_g + aoffb), (LAS unsigned*)((Pp) + tid * 16), 16, 0, 0); \
;     __builtin_amdgcn_global_load_lds((const unsigned*)(_g + (size_t)128 * lda + aoffb), (LAS unsigned*)((Pp) + tid * 16 + 8192), 16, 0, 0); } while (0)
; #define STAGE_B(Pp, br, kt) do { const char* _g = (const char*)(Bt + (size_t)(br) * K + (kt) * BK); \
;     __builtin_amdgcn_global_load_lds((const unsigned*)(_g + boffb), (LAS unsigned*)((Pp) + tid * 16), 16, 0, 0); \
;     __builtin_amdgcn_global_load_lds((const unsigned*)(_g + (size_t)128 * K + boffb), (LAS unsigned*)((Pp) + tid * 16 + 8192), 16, 0, 0); } while (0)
; #define LDA(dst, b, h) for (int m = 0; m < 4; ++m) for (int k = 0; k < 2; ++k) dst[m][k] = *(const LAS bf16x8*)(SA(b, h) + lds_byte(wr * 64 + m * 16 + fr, k * 32 + fq * 8))
; #define MMA(ai, bj, At_, Bt_) do { __builtin_amdgcn_s_setprio(1); \
;     for (int m = 0; m < 4; ++m) for (int n = 0; n < 2; ++n) for (int k = 0; k < 2; ++k) \
;         acc[ai][bj][m][n] = MFMA16(Bt_[n][k], At_[m][k], acc[ai][bj][m][n]); \
;     __builtin_amdgcn_s_setprio(0); } while (0)
; #define WAIT_V(n) asm volatile("s_waitcnt vmcnt(" #n ")" ::: "memory")
; #define WAIT_L(n) asm volatile("s_waitcnt lgkmcnt(" #n ")" ::: "memory")
; #define BAR __builtin_amdgcn_s_barrier()
; #define SCHED __builtin_amdgcn_sched_barrier(0)
; DI void gemm_phase(const Params& P, const GemmJob& J, LAS unsigned char* lds) {
;     ...
;                 LDA(At, 1, 1); STAGE_B(SB(1, 0), c2, k3); STAGE_B(SB(1, 1), c2 + HALF, k3); STAGE_A(SA(1, 0), r2, k3);
;                 WAIT_V(8); WAIT_L(0); BAR; MMA(1, 0, At, B0); MMA(1, 1, At, B1); BAR; SCHED;
;             }
	s_add_i32 s42, s20, 64
	v_lshl_add_u64 v[182:183], v[182:183], 0, s[92:93]
	s_add_i32 m0, s100, 0x18000
	s_ashr_i32 s43, s42, 31
	ds_read_b128 v[190:193], v153 offset:49152
	ds_read_b128 v[208:211], v153 offset:50176
	ds_read_b128 v[212:215], v184 offset:49152
	ds_read_b128 v[216:219], v184 offset:50176
	ds_read_b128 v[220:223], v154 offset:49152
	ds_read_b128 v[224:227], v154 offset:50176
	ds_read_b128 v[228:231], v155 offset:49152
	ds_read_b128 v[232:235], v155 offset:50176
	global_load_lds_dwordx4 v[182:183], off
	v_lshl_add_u64 v[182:183], v[236:237], 0, s[92:93]
	s_add_i32 m0, s100, 0x1a000
	s_lshl_b64 s[42:43], s[42:43], 1
	global_load_lds_dwordx4 v[182:183], off
	v_lshl_add_u64 v[182:183], v[238:239], 0, s[92:93]
	s_add_i32 m0, s100, 0x1c000
	s_add_u32 s42, s29, s42
	s_addc_u32 s43, s85, s43
	global_load_lds_dwordx4 v[182:183], off
	v_lshl_add_u64 v[182:183], v[240:241], 0, s[92:93]
	s_add_i32 m0, s100, 0x1e000
	s_nop 0
	global_load_lds_dwordx4 v[182:183], off
	s_add_i32 m0, s100, 0x8000
	s_nop 0
	global_load_lds_dwordx4 v130, s[42:43]
	s_add_u32 s42, s42, s52
	s_addc_u32 s43, s43, s53
	s_add_i32 m0, s100, 0xa000
	s_nop 0
	global_load_lds_dwordx4 v130, s[42:43]
	s_waitcnt vmcnt(8)
	s_waitcnt lgkmcnt(0)
	s_barrier
	s_setprio 1
	s_waitcnt lgkmcnt(0)
	v_mfma_f32_16x16x32_bf16 v[60:63], v[132:135], v[190:193], v[60:63]
	v_mfma_f32_16x16x32_bf16 v[52:55], v[162:165], v[190:193], v[52:55]
	v_mfma_f32_16x16x32_bf16 v[44:47], v[132:135], v[212:215], v[44:47]
	v_mfma_f32_16x16x32_bf16 v[36:39], v[162:165], v[212:215], v[36:39]
	v_mfma_f32_16x16x32_bf16 v[28:31], v[132:135], v[220:223], v[28:31]
	v_mfma_f32_16x16x32_bf16 v[20:23], v[162:165], v[220:223], v[20:23]
	v_mfma_f32_16x16x32_bf16 v[12:15], v[132:135], v[228:231], v[12:15]
	v_mfma_f32_16x16x32_bf16 v[4:7], v[162:165], v[228:231], v[4:7]
	v_mfma_f32_16x16x32_bf16 v[60:63], v[158:161], v[208:211], v[60:63]
	v_mfma_f32_16x16x32_bf16 v[52:55], v[166:169], v[208:211], v[52:55]
	v_mfma_f32_16x16x32_bf16 v[44:47], v[158:161], v[216:219], v[44:47]
	v_mfma_f32_16x16x32_bf16 v[36:39], v[166:169], v[216:219], v[36:39]
	v_mfma_f32_16x16x32_bf16 v[28:31], v[158:161], v[224:227], v[28:31]
	v_mfma_f32_16x16x32_bf16 v[20:23], v[166:169], v[224:227], v[20:23]
	v_mfma_f32_16x16x32_bf16 v[12:15], v[158:161], v[232:235], v[12:15]
	v_mfma_f32_16x16x32_bf16 v[4:7], v[166:169], v[232:235], v[4:7]
	s_setprio 0
	s_setprio 1
	v_mfma_f32_16x16x32_bf16 v[56:59], v[170:173], v[190:193], v[56:59]
	v_mfma_f32_16x16x32_bf16 v[48:51], v[178:181], v[190:193], v[48:51]
	v_mfma_f32_16x16x32_bf16 v[40:43], v[170:173], v[212:215], v[40:43]
	v_mfma_f32_16x16x32_bf16 v[32:35], v[178:181], v[212:215], v[32:35]
	v_mfma_f32_16x16x32_bf16 v[24:27], v[170:173], v[220:223], v[24:27]
	v_mfma_f32_16x16x32_bf16 v[16:19], v[178:181], v[220:223], v[16:19]
	v_mfma_f32_16x16x32_bf16 v[8:11], v[170:173], v[228:231], v[8:11]
	v_mfma_f32_16x16x32_bf16 v[0:3], v[178:181], v[228:231], v[0:3]
	v_mfma_f32_16x16x32_bf16 v[56:59], v[174:177], v[208:211], v[56:59]
	v_mfma_f32_16x16x32_bf16 v[48:51], v[186:189], v[208:211], v[48:51]
	v_mfma_f32_16x16x32_bf16 v[40:43], v[174:177], v[216:219], v[40:43]
	v_mfma_f32_16x16x32_bf16 v[32:35], v[186:189], v[216:219], v[32:35]
	v_mfma_f32_16x16x32_bf16 v[24:27], v[174:177], v[224:227], v[24:27]
	v_mfma_f32_16x16x32_bf16 v[16:19], v[186:189], v[224:227], v[16:19]
	v_mfma_f32_16x16x32_bf16 v[8:11], v[174:177], v[232:235], v[8:11]
	v_mfma_f32_16x16x32_bf16 v[0:3], v[186:189], v[232:235], v[0:3]
	s_setprio 0
	s_barrier
	s_add_i32 s95, s95, 64
	s_addk_i32 s96, 0x80
	s_add_i32 s20, s97, 2
	s_cmp_ge_u32 s97, s45
	s_mov_b32 s97, s20
	s_cbranch_scc0 .LBB0_320
	s_and_b64 vcc, exec, s[56:57]
	s_cbranch_vccz .LBB0_323
	s_barrier

; __global__ void __launch_bounds__(NTHR) fwd_megakernel(Params P) {
;     extern __shared__ __attribute__((aligned(16))) unsigned char smem_raw[];
	.amdhsa_kernel _Z14fwd_megakernel6Params
		.amdhsa_group_segment_fixed_size 0
		.amdhsa_private_segment_fixed_size 0
		.amdhsa_kernarg_size 488
		.amdhsa_user_sgpr_count 2
		.amdhsa_user_sgpr_dispatch_ptr 0
		.amdhsa_user_sgpr_queue_ptr 0
		.amdhsa_user_sgpr_kernarg_segment_ptr 1
		.amdhsa_user_sgpr_dispatch_id 0
		.amdhsa_user_sgpr_kernarg_preload_length 0
		.amdhsa_user_sgpr_kernarg_preload_offset 0
		.amdhsa_user_sgpr_private_segment_size 0
		.amdhsa_uses_dynamic_stack 0
		.amdhsa_enable_private_segment 0
		.amdhsa_system_sgpr_workgroup_id_x 1
		.amdhsa_system_sgpr_workgroup_id_y 0
		.amdhsa_system_sgpr_workgroup_id_z 0
		.amdhsa_system_sgpr_workgroup_info 0
		.amdhsa_system_vgpr_workitem_id 2
		.amdhsa_next_free_vgpr 247
		.amdhsa_next_free_sgpr 102
		.amdhsa_accum_offset 248
		.amdhsa_reserve_vcc 1
		.amdhsa_float_round_mode_32 0
		.amdhsa_float_round_mode_16_64 0
		.amdhsa_float_denorm_mode_32 3
		.amdhsa_float_denorm_mode_16_64 3
		.amdhsa_dx10_clamp 1
		.amdhsa_ieee_mode 1
		.amdhsa_fp16_overflow 0
		.amdhsa_tg_split 0
		.amdhsa_exception_fp_ieee_invalid_op 0
		.amdhsa_exception_fp_denorm_src 0
		.amdhsa_exception_fp_ieee_div_zero 0
		.amdhsa_exception_fp_ieee_overflow 0
		.amdhsa_exception_fp_ieee_underflow 0
		.amdhsa_exception_fp_ieee_inexact 0
		.amdhsa_exception_int_div_zero 0
	.end_amdhsa_kernel

amdhsa.kernels:
  - .agpr_count:     0
    .args:
      - .offset:         0
        .size:           232
        .value_kind:     by_value
      - .offset:         232
        .size:           4
        .value_kind:     hidden_block_count_x
      - .offset:         236
        .size:           4
        .value_kind:     hidden_block_count_y
      - .offset:         240
        .size:           4
        .value_kind:     hidden_block_count_z
      - .offset:         244
        .size:           2
        .value_kind:     hidden_group_size_x
      - .offset:         246
        .size:           2
        .value_kind:     hidden_group_size_y
      - .offset:         248
        .size:           2
        .value_kind:     hidden_group_size_z
      - .offset:         250
        .size:           2
        .value_kind:     hidden_remainder_x
      - .offset:         252
        .size:           2
        .value_kind:     hidden_remainder_y
      - .offset:         254
        .size:           2
        .value_kind:     hidden_remainder_z
      - .offset:         272
        .size:           8
        .value_kind:     hidden_global_offset_x
      - .offset:         280
        .size:           8
        .value_kind:     hidden_global_offset_y
      - .offset:         288
        .size:           8
        .value_kind:     hidden_global_offset_z
      - .offset:         296
        .size:           2
        .value_kind:     hidden_grid_dims
      - .offset:         320
        .size:           8
        .value_kind:     hidden_multigrid_sync_arg
      - .offset:         352
        .size:           4
        .value_kind:     hidden_dynamic_lds_size
    .group_segment_fixed_size: 0
    .kernarg_segment_align: 8
    .kernarg_segment_size: 488
    .language:       OpenCL C
    .language_version:
      - 2
      - 0
    .max_flat_workgroup_size: 512
    .name:           _Z14fwd_megakernel6Params
    .private_segment_fixed_size: 0
    .sgpr_count:     108
    .sgpr_spill_count: 168
    .symbol:         _Z14fwd_megakernel6Params.kd
    .uniform_work_group_size: 1
    .uses_dynamic_stack: false
    .vgpr_count:     247
    .vgpr_spill_count: 0
    .wavefront_size: 64
